# v16
# speedup vs baseline: 1.0050x; 1.0050x over previous
.LBB0_43:
	s_mov_b32 s1, 0
	s_add_u32 s34, s38, 0xc000000
	s_mov_b32 s29, s1
	v_mov_b32_e32 v2, v187
	s_addc_u32 s35, s39, 0
	s_lshl_b64 s[4:5], s[28:29], 9
	s_nop 0
	v_ashrrev_i32_e32 v3, 31, v2
	v_lshl_add_u64 v[2:3], s[4:5], 0, v[2:3]
	s_mov_b64 s[4:5], 0x800000
	v_cmp_gt_u64_e32 vcc, s[4:5], v[2:3]
	s_and_saveexec_b64 s[4:5], vcc
	s_cbranch_execz .LBB0_46
	v_lshlrev_b64 v[4:5], 5, v[2:3]
	v_lshl_add_u64 v[12:13], s[48:49], 0, v[4:5]
	v_lshl_add_u64 v[14:15], v[2:3], 4, s[34:35]
	s_mov_b64 s[6:7], 0x400000
	s_mov_b64 s[8:9], 0x200000
	s_mov_b32 s10, 16
.Lxconv_loop:
	global_load_dwordx4 v[16:19], v[12:13], off
	global_load_dwordx4 v[20:23], v[12:13], off offset:16
	v_lshl_add_u64 v[12:13], v[12:13], 0, s[6:7]
	global_load_dwordx4 v[24:27], v[12:13], off
	global_load_dwordx4 v[28:31], v[12:13], off offset:16
	v_lshl_add_u64 v[12:13], v[12:13], 0, s[6:7]
	global_load_dwordx4 v[32:35], v[12:13], off
	global_load_dwordx4 v[36:39], v[12:13], off offset:16
	v_lshl_add_u64 v[12:13], v[12:13], 0, s[6:7]
	global_load_dwordx4 v[40:43], v[12:13], off
	global_load_dwordx4 v[44:47], v[12:13], off offset:16
	v_lshl_add_u64 v[12:13], v[12:13], 0, s[6:7]
	s_waitcnt vmcnt(6)
	v_cvt_pk_bf16_f32 v16, v16, v17
	v_cvt_pk_bf16_f32 v17, v18, v19
	v_cvt_pk_bf16_f32 v18, v20, v21
	v_cvt_pk_bf16_f32 v19, v22, v23
	global_store_dwordx4 v[14:15], v[16:19], off
	v_lshl_add_u64 v[14:15], v[14:15], 0, s[8:9]
	s_waitcnt vmcnt(5)
	v_cvt_pk_bf16_f32 v24, v24, v25
	v_cvt_pk_bf16_f32 v25, v26, v27
	v_cvt_pk_bf16_f32 v26, v28, v29
	v_cvt_pk_bf16_f32 v27, v30, v31
	global_store_dwordx4 v[14:15], v[24:27], off
	v_lshl_add_u64 v[14:15], v[14:15], 0, s[8:9]
	s_waitcnt vmcnt(4)
	v_cvt_pk_bf16_f32 v32, v32, v33
	v_cvt_pk_bf16_f32 v33, v34, v35
	v_cvt_pk_bf16_f32 v34, v36, v37
	v_cvt_pk_bf16_f32 v35, v38, v39
	global_store_dwordx4 v[14:15], v[32:35], off
	v_lshl_add_u64 v[14:15], v[14:15], 0, s[8:9]
	s_waitcnt vmcnt(3)
	v_cvt_pk_bf16_f32 v40, v40, v41
	v_cvt_pk_bf16_f32 v41, v42, v43
	v_cvt_pk_bf16_f32 v42, v44, v45
	v_cvt_pk_bf16_f32 v43, v46, v47
	global_store_dwordx4 v[14:15], v[40:43], off
	v_lshl_add_u64 v[14:15], v[14:15], 0, s[8:9]
	s_sub_i32 s10, s10, 1
	s_cmp_lg_u32 s10, 0
	s_cbranch_scc1 .Lxconv_loop
